# hgrn_h1: second k-step's nine LDS fragment reads issued together under the first step's last MFMAs, counted lgkmcnt (was read->wait->MFMA x8)
# baseline (speedup 1.0000x reference)
; #define LAS __attribute__((address_space(3)))
; __device__ __forceinline__ void hgrn_h1(LAS unsigned char* lds8, const int e) {
;     ...
;         f32x4 acc[8];
; #pragma unroll
;         for (int nt = 0; nt < 8; ++nt) acc[nt] = (f32x4){0.f, 0.f, 0.f, 0.f};
;         const int fr = lane & 15, fq = lane >> 4;
; #pragma unroll
;         for (int s = 0; s < 2; ++s) {
;             const bf16x8 a = *(const LAS bf16x8*)(KhT + (16 * wave + fr) * RS64 + 32 * s + 8 * fq);
; #pragma unroll
;             for (int nt = 0; nt < 8; ++nt) { const bf16x8 bb = *(const LAS bf16x8*)(VT + (16 * nt + fr) * RS64 + 32 * s + 8 * fq);
;                 acc[nt] = __builtin_amdgcn_mfma_f32_16x16x32_bf16(a, bb, acc[nt], 0, 0, 0); }
;         }
;         float* Lo = LBUF + (size_t)item * 16384 + (size_t)(16 * wave + 4 * fq) * 128 + fr;
; #pragma unroll
;         for (int nt = 0; nt < 8; ++nt)
; #pragma unroll
;             for (int r = 0; r < 4; ++r) Lo[r * 128 + 16 * nt] = acc[nt][r];
.LBB0_1014:
	s_or_b64 exec, exec, s[10:11]
	s_waitcnt lgkmcnt(0)
	s_barrier
	ds_read_b128 v[12:15], v4
	ds_read_b128 v[16:19], v32 offset:18432
	ds_read_b128 v[20:23], v32 offset:20736
	ds_read_b128 v[50:53], v32 offset:34560
	ds_read_b128 v[24:27], v32 offset:23040
	ds_read_b128 v[34:37], v32 offset:25344
	ds_read_b128 v[38:41], v32 offset:27648
	ds_read_b128 v[42:45], v32 offset:29952
	ds_read_b128 v[46:49], v32 offset:32256
	s_waitcnt lgkmcnt(7)
	v_mfma_f32_16x16x32_bf16 v[16:19], v[12:15], v[16:19], 0
	s_add_i32 s2, s2, s12
	s_add_i32 s4, s4, s5
	s_add_i32 s26, s26, s27
	s_waitcnt lgkmcnt(6)
	v_mfma_f32_16x16x32_bf16 v[20:23], v[12:15], v[20:23], 0
	v_lshl_add_u64 v[6:7], v[6:7], 0, s[16:17]
	s_cmpk_lt_i32 s2, 0x400
	s_waitcnt lgkmcnt(4)
	v_mfma_f32_16x16x32_bf16 v[24:27], v[12:15], v[24:27], 0
	s_waitcnt lgkmcnt(3)
	v_mfma_f32_16x16x32_bf16 v[34:37], v[12:15], v[34:37], 0
	s_waitcnt lgkmcnt(2)
	v_mfma_f32_16x16x32_bf16 v[38:41], v[12:15], v[38:41], 0
	s_waitcnt lgkmcnt(1)
	v_mfma_f32_16x16x32_bf16 v[42:45], v[12:15], v[42:45], 0
	s_waitcnt lgkmcnt(0)
	ds_read_b128 v[70:73], v4 offset:64
	ds_read_b128 v[74:77], v32 offset:18496
	ds_read_b128 v[78:81], v32 offset:20800
	ds_read_b128 v[82:85], v32 offset:23104
	ds_read_b128 v[86:89], v32 offset:25408
	ds_read_b128 v[90:93], v32 offset:27712
	ds_read_b128 v[94:97], v32 offset:30016
	ds_read_b128 v[98:101], v32 offset:32320
	ds_read_b128 v[102:105], v32 offset:34624
	v_mfma_f32_16x16x32_bf16 v[46:49], v[12:15], v[46:49], 0
	v_mfma_f32_16x16x32_bf16 v[12:15], v[12:15], v[50:53], 0
	s_waitcnt lgkmcnt(7)
	v_mfma_f32_16x16x32_bf16 v[16:19], v[70:73], v[74:77], v[16:19]
	s_waitcnt lgkmcnt(6)
	v_mfma_f32_16x16x32_bf16 v[20:23], v[70:73], v[78:81], v[20:23]
	s_waitcnt lgkmcnt(5)
	v_mfma_f32_16x16x32_bf16 v[24:27], v[70:73], v[82:85], v[24:27]
	s_waitcnt lgkmcnt(4)
	v_mfma_f32_16x16x32_bf16 v[34:37], v[70:73], v[86:89], v[34:37]
	s_waitcnt lgkmcnt(3)
	v_mfma_f32_16x16x32_bf16 v[38:41], v[70:73], v[90:93], v[38:41]
	s_waitcnt lgkmcnt(2)
	v_mfma_f32_16x16x32_bf16 v[42:45], v[70:73], v[94:97], v[42:45]
	s_waitcnt lgkmcnt(1)
	v_mfma_f32_16x16x32_bf16 v[46:49], v[70:73], v[98:101], v[46:49]
	s_waitcnt lgkmcnt(0)
	v_mfma_f32_16x16x32_bf16 v[12:15], v[70:73], v[102:105], v[12:15]
	global_store_dword v[8:9], v16, off offset:-1024
	global_store_dword v[8:9], v17, off offset:-512
	global_store_dword v[8:9], v18, off
	global_store_dword v[8:9], v19, off offset:512
	global_store_dword v[8:9], v20, off offset:-960
	global_store_dword v[8:9], v21, off offset:-448
	global_store_dword v[8:9], v22, off offset:64
	global_store_dword v[8:9], v23, off offset:576
	global_store_dword v[8:9], v24, off offset:-896
	global_store_dword v[8:9], v25, off offset:-384
	global_store_dword v[8:9], v26, off offset:128
	global_store_dword v[8:9], v27, off offset:640
	global_store_dword v[8:9], v34, off offset:-832
	global_store_dword v[8:9], v35, off offset:-320
	global_store_dword v[8:9], v36, off offset:192
	global_store_dword v[8:9], v37, off offset:704
	global_store_dword v[8:9], v38, off offset:-768
	global_store_dword v[8:9], v39, off offset:-256
	global_store_dword v[8:9], v40, off offset:256
	global_store_dword v[8:9], v41, off offset:768
	global_store_dword v[8:9], v42, off offset:-704
	global_store_dword v[8:9], v43, off offset:-192
	global_store_dword v[8:9], v44, off offset:320
	global_store_dword v[8:9], v45, off offset:832
	global_store_dword v[8:9], v46, off offset:-640
	global_store_dword v[8:9], v47, off offset:-128
	global_store_dword v[8:9], v48, off offset:384
	global_store_dword v[8:9], v49, off offset:896
	global_store_dword v[8:9], v12, off offset:-576
	global_store_dword v[8:9], v13, off offset:-64
	global_store_dword v[8:9], v14, off offset:448
	global_store_dword v[8:9], v15, off offset:960
	v_lshl_add_u64 v[8:9], v[8:9], 0, s[18:19]
	s_cbranch_scc0 .LBB0_1031
